# G2 rescale epilogue: the 16 gate loads of the first half requested up front (was four serial round trips)
# baseline (speedup 1.0000x reference)
.LBB0_1240:
	v_add_co_u32_e32 v210, vcc, 0x1000, v2
	s_nop 1
	v_addc_co_u32_e32 v211, vcc, 0, v3, vcc
	global_load_dwordx4 v[192:195], v[210:211], off offset:-4096
	global_load_dwordx4 v[188:191], v[210:211], off
	global_load_dwordx4 v[184:187], v[210:211], off offset:-3840
	global_load_dwordx4 v[180:183], v[210:211], off offset:256
	v_add_co_u32_e32 v210, vcc, 0x7c000, v210
	s_nop 1
	v_addc_co_u32_e32 v211, vcc, 0, v211, vcc
	global_load_dwordx4 v[172:175], v[210:211], off offset:-4096
	global_load_dwordx4 v[176:179], v[210:211], off
	global_load_dwordx4 v[168:171], v[210:211], off offset:-3840
	global_load_dwordx4 v[164:167], v[210:211], off offset:256
	v_add_co_u32_e32 v210, vcc, 0x7c000, v210
	s_nop 1
	v_addc_co_u32_e32 v211, vcc, 0, v211, vcc
	global_load_dwordx4 v[156:159], v[210:211], off offset:-4096
	global_load_dwordx4 v[160:163], v[210:211], off
	global_load_dwordx4 v[152:155], v[210:211], off offset:-3840
	global_load_dwordx4 v[148:151], v[210:211], off offset:256
	v_add_co_u32_e32 v210, vcc, 0x7c000, v210
	s_nop 1
	v_addc_co_u32_e32 v211, vcc, 0, v211, vcc
	global_load_dwordx4 v[140:143], v[210:211], off offset:-4096
	global_load_dwordx4 v[144:147], v[210:211], off
	global_load_dwordx4 v[132:135], v[210:211], off offset:-3840
	global_load_dwordx4 v[136:139], v[210:211], off offset:256
	s_nop 0
	s_nop 0
	s_mov_b32 s0, 0x174000
	s_nop 0
	s_nop 0
	s_nop 0
	s_nop 0
	s_nop 0
	s_nop 0
	s_waitcnt vmcnt(12)
	v_lshlrev_b32_e32 v0, 16, v192
	v_max_f32_e32 v0, v0, v0
	v_max_f32_e32 v210, 0x1e3ce508, v0
	s_nop 0
	v_lshlrev_b32_e32 v0, 16, v188
	v_max_f32_e32 v0, v0, v0
	v_max_f32_e32 v0, 0x1e3ce508, v0
	v_rcp_f32_e32 v212, v0
	v_and_b32_e32 v0, 0xffff0000, v192
	s_nop 0
	v_max_f32_e32 v0, v0, v0
	v_max_f32_e32 v211, 0x1e3ce508, v0
	v_and_b32_e32 v0, 0xffff0000, v188
	s_nop 0
	v_max_f32_e32 v0, v0, v0
	s_nop 0
	s_nop 0
	v_max_f32_e32 v0, 0x1e3ce508, v0
	s_nop 0
	s_nop 0
	s_nop 0
	v_rcp_f32_e32 v213, v0
	v_lshlrev_b32_e32 v0, 16, v193
	v_max_f32_e32 v0, v0, v0
	v_max_f32_e32 v192, 0x1e3ce508, v0
	v_lshlrev_b32_e32 v0, 16, v189
	v_max_f32_e32 v0, v0, v0
	v_max_f32_e32 v0, 0x1e3ce508, v0
	v_rcp_f32_e32 v188, v0
	v_and_b32_e32 v0, 0xffff0000, v193
	v_max_f32_e32 v0, v0, v0
	v_max_f32_e32 v193, 0x1e3ce508, v0
	v_and_b32_e32 v0, 0xffff0000, v189
	v_max_f32_e32 v0, v0, v0
	v_max_f32_e32 v0, 0x1e3ce508, v0
	v_rcp_f32_e32 v189, v0
	v_lshlrev_b32_e32 v0, 16, v194
	v_max_f32_e32 v0, v0, v0
	s_nop 0
	v_pk_mul_f32 v[188:189], v[192:193], v[188:189]
	s_nop 0
	s_nop 0
	v_pk_mul_f32 v[130:131], v[130:131], v[188:189]
	v_max_f32_e32 v188, 0x1e3ce508, v0
	v_lshlrev_b32_e32 v0, 16, v190
	v_max_f32_e32 v0, v0, v0
	v_max_f32_e32 v0, 0x1e3ce508, v0
	v_rcp_f32_e32 v192, v0
	v_and_b32_e32 v0, 0xffff0000, v194
	v_max_f32_e32 v0, v0, v0
	v_max_f32_e32 v189, 0x1e3ce508, v0
	v_and_b32_e32 v0, 0xffff0000, v190
	v_max_f32_e32 v0, v0, v0
	v_max_f32_e32 v0, 0x1e3ce508, v0
	v_rcp_f32_e32 v193, v0
	v_lshlrev_b32_e32 v0, 16, v195
	v_max_f32_e32 v0, v0, v0
	v_max_f32_e32 v194, 0x1e3ce508, v0
	v_lshlrev_b32_e32 v0, 16, v191
	v_max_f32_e32 v0, v0, v0
	v_max_f32_e32 v0, 0x1e3ce508, v0
	v_rcp_f32_e32 v190, v0
	v_and_b32_e32 v0, 0xffff0000, v195
	v_max_f32_e32 v0, v0, v0
	v_max_f32_e32 v195, 0x1e3ce508, v0
	v_and_b32_e32 v0, 0xffff0000, v191
	v_max_f32_e32 v0, v0, v0
	v_max_f32_e32 v0, 0x1e3ce508, v0
	v_rcp_f32_e32 v191, v0
	v_lshlrev_b32_e32 v0, 16, v184
	v_pk_mul_f32 v[188:189], v[188:189], v[192:193]
	v_max_f32_e32 v0, v0, v0
	v_pk_mul_f32 v[124:125], v[124:125], v[188:189]
	v_max_f32_e32 v188, 0x1e3ce508, v0
	v_lshlrev_b32_e32 v0, 16, v180
	v_max_f32_e32 v0, v0, v0
	v_pk_mul_f32 v[190:191], v[194:195], v[190:191]
	v_max_f32_e32 v0, 0x1e3ce508, v0
	v_pk_mul_f32 v[126:127], v[126:127], v[190:191]
	v_rcp_f32_e32 v190, v0
	v_and_b32_e32 v0, 0xffff0000, v184
	v_max_f32_e32 v0, v0, v0
	v_max_f32_e32 v189, 0x1e3ce508, v0
	v_and_b32_e32 v0, 0xffff0000, v180
	v_max_f32_e32 v0, v0, v0
	v_max_f32_e32 v0, 0x1e3ce508, v0
	v_rcp_f32_e32 v191, v0
	v_lshlrev_b32_e32 v0, 16, v185
	v_max_f32_e32 v0, v0, v0
	v_max_f32_e32 v184, 0x1e3ce508, v0
	v_lshlrev_b32_e32 v0, 16, v181
	v_max_f32_e32 v0, v0, v0
	v_max_f32_e32 v0, 0x1e3ce508, v0
	v_rcp_f32_e32 v180, v0
	v_and_b32_e32 v0, 0xffff0000, v185
	v_max_f32_e32 v0, v0, v0
	v_max_f32_e32 v185, 0x1e3ce508, v0
	v_and_b32_e32 v0, 0xffff0000, v181
	v_max_f32_e32 v0, v0, v0
	v_max_f32_e32 v0, 0x1e3ce508, v0
	v_rcp_f32_e32 v181, v0
	v_lshlrev_b32_e32 v0, 16, v186
	v_max_f32_e32 v0, v0, v0
	s_nop 0
	v_pk_mul_f32 v[180:181], v[184:185], v[180:181]
	s_nop 0
	v_pk_mul_f32 v[98:99], v[98:99], v[180:181]
	v_max_f32_e32 v180, 0x1e3ce508, v0
	v_lshlrev_b32_e32 v0, 16, v182
	v_max_f32_e32 v0, v0, v0
	v_max_f32_e32 v0, 0x1e3ce508, v0
	v_rcp_f32_e32 v184, v0
	v_and_b32_e32 v0, 0xffff0000, v186
	v_max_f32_e32 v0, v0, v0
	v_max_f32_e32 v181, 0x1e3ce508, v0
	v_and_b32_e32 v0, 0xffff0000, v182
	v_max_f32_e32 v0, v0, v0
	v_max_f32_e32 v0, 0x1e3ce508, v0
	v_rcp_f32_e32 v185, v0
	v_lshlrev_b32_e32 v0, 16, v187
	v_max_f32_e32 v0, v0, v0
	v_max_f32_e32 v186, 0x1e3ce508, v0
	v_lshlrev_b32_e32 v0, 16, v183
	v_max_f32_e32 v0, v0, v0
	v_max_f32_e32 v0, 0x1e3ce508, v0
	v_rcp_f32_e32 v182, v0
	v_and_b32_e32 v0, 0xffff0000, v187
	v_max_f32_e32 v0, v0, v0
	v_max_f32_e32 v187, 0x1e3ce508, v0
	v_and_b32_e32 v0, 0xffff0000, v183
	v_max_f32_e32 v0, v0, v0
	v_max_f32_e32 v0, 0x1e3ce508, v0
	v_rcp_f32_e32 v183, v0
	s_waitcnt vmcnt(7)
	v_lshlrev_b32_e32 v0, 16, v172
	v_pk_mul_f32 v[180:181], v[180:181], v[184:185]
	v_max_f32_e32 v0, v0, v0
	v_pk_mul_f32 v[92:93], v[92:93], v[180:181]
	v_max_f32_e32 v180, 0x1e3ce508, v0
	v_lshlrev_b32_e32 v0, 16, v176
	v_max_f32_e32 v0, v0, v0
	v_pk_mul_f32 v[182:183], v[186:187], v[182:183]
	v_max_f32_e32 v0, 0x1e3ce508, v0
	v_pk_mul_f32 v[94:95], v[94:95], v[182:183]
	v_rcp_f32_e32 v182, v0
	v_and_b32_e32 v0, 0xffff0000, v172
	v_max_f32_e32 v0, v0, v0
	v_max_f32_e32 v181, 0x1e3ce508, v0
	v_and_b32_e32 v0, 0xffff0000, v176
	v_max_f32_e32 v0, v0, v0
	s_nop 0
	v_max_f32_e32 v0, 0x1e3ce508, v0
	s_nop 0
	s_nop 0
	s_nop 0
	v_rcp_f32_e32 v183, v0
	v_lshlrev_b32_e32 v0, 16, v173
	v_max_f32_e32 v0, v0, v0
	v_max_f32_e32 v172, 0x1e3ce508, v0
	v_lshlrev_b32_e32 v0, 16, v177
	v_max_f32_e32 v0, v0, v0
	v_max_f32_e32 v0, 0x1e3ce508, v0
	v_rcp_f32_e32 v176, v0
	v_and_b32_e32 v0, 0xffff0000, v173
	v_max_f32_e32 v0, v0, v0
	v_max_f32_e32 v173, 0x1e3ce508, v0
	v_and_b32_e32 v0, 0xffff0000, v177
	v_max_f32_e32 v0, v0, v0
	v_max_f32_e32 v0, 0x1e3ce508, v0
	v_rcp_f32_e32 v177, v0
	v_lshlrev_b32_e32 v0, 16, v174
	v_max_f32_e32 v0, v0, v0
	s_nop 0
	v_pk_mul_f32 v[172:173], v[172:173], v[176:177]
	s_nop 0
	s_nop 0
	v_pk_mul_f32 v[122:123], v[122:123], v[172:173]
	v_max_f32_e32 v172, 0x1e3ce508, v0
	v_lshlrev_b32_e32 v0, 16, v178
	v_max_f32_e32 v0, v0, v0
	v_max_f32_e32 v0, 0x1e3ce508, v0
	v_rcp_f32_e32 v176, v0
	v_and_b32_e32 v0, 0xffff0000, v174
	v_max_f32_e32 v0, v0, v0
	v_max_f32_e32 v173, 0x1e3ce508, v0
	v_and_b32_e32 v0, 0xffff0000, v178
	v_max_f32_e32 v0, v0, v0
	v_max_f32_e32 v0, 0x1e3ce508, v0
	v_rcp_f32_e32 v177, v0
	v_lshlrev_b32_e32 v0, 16, v175
	v_max_f32_e32 v0, v0, v0
	v_max_f32_e32 v174, 0x1e3ce508, v0
	v_lshlrev_b32_e32 v0, 16, v179
	v_max_f32_e32 v0, v0, v0
	v_max_f32_e32 v0, 0x1e3ce508, v0
	v_rcp_f32_e32 v178, v0
	v_and_b32_e32 v0, 0xffff0000, v175
	v_max_f32_e32 v0, v0, v0
	v_max_f32_e32 v175, 0x1e3ce508, v0
	v_and_b32_e32 v0, 0xffff0000, v179
	v_max_f32_e32 v0, v0, v0
	v_max_f32_e32 v0, 0x1e3ce508, v0
	v_rcp_f32_e32 v179, v0
	v_lshlrev_b32_e32 v0, 16, v168
	v_pk_mul_f32 v[172:173], v[172:173], v[176:177]
	v_max_f32_e32 v0, v0, v0
	v_pk_mul_f32 v[116:117], v[116:117], v[172:173]
	v_max_f32_e32 v172, 0x1e3ce508, v0
	v_lshlrev_b32_e32 v0, 16, v164
	v_max_f32_e32 v0, v0, v0
	v_pk_mul_f32 v[174:175], v[174:175], v[178:179]
	v_max_f32_e32 v0, 0x1e3ce508, v0
	v_pk_mul_f32 v[118:119], v[118:119], v[174:175]
	v_rcp_f32_e32 v174, v0
	v_and_b32_e32 v0, 0xffff0000, v168
	v_max_f32_e32 v0, v0, v0
	v_max_f32_e32 v173, 0x1e3ce508, v0
	v_and_b32_e32 v0, 0xffff0000, v164
	v_max_f32_e32 v0, v0, v0
	v_max_f32_e32 v0, 0x1e3ce508, v0
	v_rcp_f32_e32 v175, v0
	v_lshlrev_b32_e32 v0, 16, v169
	v_max_f32_e32 v0, v0, v0
	v_max_f32_e32 v168, 0x1e3ce508, v0
	v_lshlrev_b32_e32 v0, 16, v165
	v_max_f32_e32 v0, v0, v0
	v_max_f32_e32 v0, 0x1e3ce508, v0
	v_rcp_f32_e32 v164, v0
	v_and_b32_e32 v0, 0xffff0000, v169
	v_max_f32_e32 v0, v0, v0
	v_max_f32_e32 v169, 0x1e3ce508, v0
	v_and_b32_e32 v0, 0xffff0000, v165
	v_max_f32_e32 v0, v0, v0
	v_max_f32_e32 v0, 0x1e3ce508, v0
	v_rcp_f32_e32 v165, v0
	v_lshlrev_b32_e32 v0, 16, v170
	v_max_f32_e32 v0, v0, v0
	s_nop 0
	v_pk_mul_f32 v[164:165], v[168:169], v[164:165]
	s_nop 0
	v_pk_mul_f32 v[90:91], v[90:91], v[164:165]
	v_max_f32_e32 v164, 0x1e3ce508, v0
	v_lshlrev_b32_e32 v0, 16, v166
	v_max_f32_e32 v0, v0, v0
	v_max_f32_e32 v0, 0x1e3ce508, v0
	v_rcp_f32_e32 v168, v0
	v_and_b32_e32 v0, 0xffff0000, v170
	v_max_f32_e32 v0, v0, v0
	v_max_f32_e32 v165, 0x1e3ce508, v0
	v_and_b32_e32 v0, 0xffff0000, v166
	v_max_f32_e32 v0, v0, v0
	v_max_f32_e32 v0, 0x1e3ce508, v0
	v_rcp_f32_e32 v169, v0
	v_lshlrev_b32_e32 v0, 16, v171
	v_max_f32_e32 v0, v0, v0
	v_max_f32_e32 v170, 0x1e3ce508, v0
	v_lshlrev_b32_e32 v0, 16, v167
	v_max_f32_e32 v0, v0, v0
	v_max_f32_e32 v0, 0x1e3ce508, v0
	v_rcp_f32_e32 v166, v0
	v_and_b32_e32 v0, 0xffff0000, v171
	v_max_f32_e32 v0, v0, v0
	v_max_f32_e32 v171, 0x1e3ce508, v0
	v_and_b32_e32 v0, 0xffff0000, v167
	v_max_f32_e32 v0, v0, v0
	v_max_f32_e32 v0, 0x1e3ce508, v0
	v_rcp_f32_e32 v167, v0
	v_lshlrev_b32_e32 v0, 16, v156
	v_pk_mul_f32 v[164:165], v[164:165], v[168:169]
	v_max_f32_e32 v0, v0, v0
	v_pk_mul_f32 v[84:85], v[84:85], v[164:165]
	v_max_f32_e32 v164, 0x1e3ce508, v0
	s_waitcnt vmcnt(3)
	v_lshlrev_b32_e32 v0, 16, v160
	v_max_f32_e32 v0, v0, v0
	v_pk_mul_f32 v[166:167], v[170:171], v[166:167]
	v_max_f32_e32 v0, 0x1e3ce508, v0
	v_pk_mul_f32 v[86:87], v[86:87], v[166:167]
	v_rcp_f32_e32 v166, v0
	v_and_b32_e32 v0, 0xffff0000, v156
	v_max_f32_e32 v0, v0, v0
	v_max_f32_e32 v165, 0x1e3ce508, v0
	v_and_b32_e32 v0, 0xffff0000, v160
	v_max_f32_e32 v0, v0, v0
	s_nop 0
	v_max_f32_e32 v0, 0x1e3ce508, v0
	s_nop 0
	s_nop 0
	s_nop 0
	s_nop 0
	s_nop 0
	v_rcp_f32_e32 v167, v0
	v_lshlrev_b32_e32 v0, 16, v157
	v_max_f32_e32 v0, v0, v0
	v_max_f32_e32 v156, 0x1e3ce508, v0
	v_lshlrev_b32_e32 v0, 16, v161
	v_max_f32_e32 v0, v0, v0
	v_max_f32_e32 v0, 0x1e3ce508, v0
	v_rcp_f32_e32 v160, v0
	v_and_b32_e32 v0, 0xffff0000, v157
	v_max_f32_e32 v0, v0, v0
	v_max_f32_e32 v157, 0x1e3ce508, v0
	v_and_b32_e32 v0, 0xffff0000, v161
	v_max_f32_e32 v0, v0, v0
	v_max_f32_e32 v0, 0x1e3ce508, v0
	v_rcp_f32_e32 v161, v0
	v_lshlrev_b32_e32 v0, 16, v158
	v_max_f32_e32 v0, v0, v0
	s_mov_b32 s0, 0x3e0000
	v_pk_mul_f32 v[156:157], v[156:157], v[160:161]
	v_pk_mul_f32 v[188:189], v[188:189], v[190:191]
	v_pk_mul_f32 v[114:115], v[114:115], v[156:157]
	v_max_f32_e32 v156, 0x1e3ce508, v0
	v_lshlrev_b32_e32 v0, 16, v162
	v_max_f32_e32 v0, v0, v0
	v_max_f32_e32 v0, 0x1e3ce508, v0
	v_rcp_f32_e32 v160, v0
	v_and_b32_e32 v0, 0xffff0000, v158
	v_max_f32_e32 v0, v0, v0
	v_max_f32_e32 v157, 0x1e3ce508, v0
	v_and_b32_e32 v0, 0xffff0000, v162
	v_max_f32_e32 v0, v0, v0
	v_max_f32_e32 v0, 0x1e3ce508, v0
	v_rcp_f32_e32 v161, v0
	v_lshlrev_b32_e32 v0, 16, v159
	v_max_f32_e32 v0, v0, v0
	v_max_f32_e32 v158, 0x1e3ce508, v0
	v_lshlrev_b32_e32 v0, 16, v163
	v_max_f32_e32 v0, v0, v0
	v_max_f32_e32 v0, 0x1e3ce508, v0
	v_rcp_f32_e32 v162, v0
	v_and_b32_e32 v0, 0xffff0000, v159
	v_max_f32_e32 v0, v0, v0
	v_max_f32_e32 v159, 0x1e3ce508, v0
	v_and_b32_e32 v0, 0xffff0000, v163
	v_max_f32_e32 v0, v0, v0
	v_max_f32_e32 v0, 0x1e3ce508, v0
	v_rcp_f32_e32 v163, v0
	v_lshlrev_b32_e32 v0, 16, v152
	v_pk_mul_f32 v[156:157], v[156:157], v[160:161]
	v_max_f32_e32 v0, v0, v0
	v_pk_mul_f32 v[108:109], v[108:109], v[156:157]
	v_max_f32_e32 v156, 0x1e3ce508, v0
	v_lshlrev_b32_e32 v0, 16, v148
	v_max_f32_e32 v0, v0, v0
	v_pk_mul_f32 v[158:159], v[158:159], v[162:163]
	v_max_f32_e32 v0, 0x1e3ce508, v0
	v_pk_mul_f32 v[110:111], v[110:111], v[158:159]
	v_rcp_f32_e32 v158, v0
	v_and_b32_e32 v0, 0xffff0000, v152
	v_max_f32_e32 v0, v0, v0
	v_max_f32_e32 v157, 0x1e3ce508, v0
	v_and_b32_e32 v0, 0xffff0000, v148
	v_max_f32_e32 v0, v0, v0
	v_max_f32_e32 v0, 0x1e3ce508, v0
	v_rcp_f32_e32 v159, v0
	v_lshlrev_b32_e32 v0, 16, v153
	v_max_f32_e32 v0, v0, v0
	v_max_f32_e32 v152, 0x1e3ce508, v0
	v_lshlrev_b32_e32 v0, 16, v149
	v_max_f32_e32 v0, v0, v0
	v_max_f32_e32 v0, 0x1e3ce508, v0
	v_rcp_f32_e32 v148, v0
	v_and_b32_e32 v0, 0xffff0000, v153
	v_max_f32_e32 v0, v0, v0
	v_max_f32_e32 v153, 0x1e3ce508, v0
	v_and_b32_e32 v0, 0xffff0000, v149
	v_max_f32_e32 v0, v0, v0
	v_max_f32_e32 v0, 0x1e3ce508, v0
	v_rcp_f32_e32 v149, v0
	v_lshlrev_b32_e32 v0, 16, v154
	v_max_f32_e32 v0, v0, v0
	v_pk_mul_f32 v[172:173], v[172:173], v[174:175]
	v_pk_mul_f32 v[148:149], v[152:153], v[148:149]
	v_pk_mul_f32 v[96:97], v[96:97], v[188:189]
	v_pk_mul_f32 v[82:83], v[82:83], v[148:149]
	v_max_f32_e32 v148, 0x1e3ce508, v0
	v_lshlrev_b32_e32 v0, 16, v150
	v_max_f32_e32 v0, v0, v0
	v_max_f32_e32 v0, 0x1e3ce508, v0
	v_rcp_f32_e32 v152, v0
	v_and_b32_e32 v0, 0xffff0000, v154
	v_max_f32_e32 v0, v0, v0
	v_max_f32_e32 v149, 0x1e3ce508, v0
	v_and_b32_e32 v0, 0xffff0000, v150
	v_max_f32_e32 v0, v0, v0
	v_max_f32_e32 v0, 0x1e3ce508, v0
	v_rcp_f32_e32 v153, v0
	v_lshlrev_b32_e32 v0, 16, v155
	v_max_f32_e32 v0, v0, v0
	v_max_f32_e32 v154, 0x1e3ce508, v0
	v_lshlrev_b32_e32 v0, 16, v151
	v_max_f32_e32 v0, v0, v0
	v_max_f32_e32 v0, 0x1e3ce508, v0
	v_rcp_f32_e32 v150, v0
	v_and_b32_e32 v0, 0xffff0000, v155
	v_max_f32_e32 v0, v0, v0
	v_max_f32_e32 v155, 0x1e3ce508, v0
	v_and_b32_e32 v0, 0xffff0000, v151
	v_max_f32_e32 v0, v0, v0
	v_max_f32_e32 v0, 0x1e3ce508, v0
	v_rcp_f32_e32 v151, v0
	v_lshlrev_b32_e32 v0, 16, v140
	v_pk_mul_f32 v[148:149], v[148:149], v[152:153]
	v_max_f32_e32 v0, v0, v0
	v_pk_mul_f32 v[76:77], v[76:77], v[148:149]
	v_max_f32_e32 v148, 0x1e3ce508, v0
	s_waitcnt vmcnt(0)
	v_lshlrev_b32_e32 v0, 16, v144
	v_max_f32_e32 v0, v0, v0
	v_pk_mul_f32 v[150:151], v[154:155], v[150:151]
	v_max_f32_e32 v0, 0x1e3ce508, v0
	v_pk_mul_f32 v[78:79], v[78:79], v[150:151]
	v_rcp_f32_e32 v150, v0
	v_and_b32_e32 v0, 0xffff0000, v140
	v_max_f32_e32 v0, v0, v0
	v_max_f32_e32 v149, 0x1e3ce508, v0
	v_and_b32_e32 v0, 0xffff0000, v144
	v_max_f32_e32 v0, v0, v0
	v_max_f32_e32 v0, 0x1e3ce508, v0
	v_rcp_f32_e32 v151, v0
	v_lshlrev_b32_e32 v0, 16, v141
	v_max_f32_e32 v0, v0, v0
	v_max_f32_e32 v140, 0x1e3ce508, v0
	v_lshlrev_b32_e32 v0, 16, v145
	v_max_f32_e32 v0, v0, v0
	v_max_f32_e32 v0, 0x1e3ce508, v0
	v_rcp_f32_e32 v144, v0
	v_and_b32_e32 v0, 0xffff0000, v141
	v_max_f32_e32 v0, v0, v0
	v_max_f32_e32 v141, 0x1e3ce508, v0
	v_and_b32_e32 v0, 0xffff0000, v145
	v_max_f32_e32 v0, v0, v0
	v_max_f32_e32 v0, 0x1e3ce508, v0
	v_rcp_f32_e32 v145, v0
	v_lshlrev_b32_e32 v0, 16, v142
	v_max_f32_e32 v0, v0, v0
	v_pk_mul_f32 v[88:89], v[88:89], v[172:173]
	v_pk_mul_f32 v[140:141], v[140:141], v[144:145]
	v_pk_mul_f32 v[180:181], v[180:181], v[182:183]
	v_pk_mul_f32 v[106:107], v[106:107], v[140:141]
	v_max_f32_e32 v140, 0x1e3ce508, v0
	v_lshlrev_b32_e32 v0, 16, v146
	v_max_f32_e32 v0, v0, v0
	v_max_f32_e32 v0, 0x1e3ce508, v0
	v_rcp_f32_e32 v144, v0
	v_and_b32_e32 v0, 0xffff0000, v142
	v_max_f32_e32 v0, v0, v0
	v_max_f32_e32 v141, 0x1e3ce508, v0
	v_and_b32_e32 v0, 0xffff0000, v146
	v_max_f32_e32 v0, v0, v0
	v_max_f32_e32 v0, 0x1e3ce508, v0
	v_rcp_f32_e32 v145, v0
	v_lshlrev_b32_e32 v0, 16, v143
	v_max_f32_e32 v0, v0, v0
	v_max_f32_e32 v142, 0x1e3ce508, v0
	v_lshlrev_b32_e32 v0, 16, v147
	v_max_f32_e32 v0, v0, v0
	v_max_f32_e32 v0, 0x1e3ce508, v0
	v_rcp_f32_e32 v146, v0
	v_and_b32_e32 v0, 0xffff0000, v143
	v_max_f32_e32 v0, v0, v0
	v_max_f32_e32 v143, 0x1e3ce508, v0
	v_and_b32_e32 v0, 0xffff0000, v147
	v_max_f32_e32 v0, v0, v0
	v_max_f32_e32 v0, 0x1e3ce508, v0
	v_rcp_f32_e32 v147, v0
	v_lshlrev_b32_e32 v0, 16, v132
	v_pk_mul_f32 v[140:141], v[140:141], v[144:145]
	v_max_f32_e32 v0, v0, v0
	v_pk_mul_f32 v[100:101], v[100:101], v[140:141]
	v_max_f32_e32 v140, 0x1e3ce508, v0
	v_lshlrev_b32_e32 v0, 16, v136
	v_max_f32_e32 v0, v0, v0
	v_pk_mul_f32 v[142:143], v[142:143], v[146:147]
	v_max_f32_e32 v0, 0x1e3ce508, v0
	v_pk_mul_f32 v[102:103], v[102:103], v[142:143]
	v_rcp_f32_e32 v142, v0
	v_and_b32_e32 v0, 0xffff0000, v132
	v_max_f32_e32 v0, v0, v0
	v_max_f32_e32 v141, 0x1e3ce508, v0
	v_and_b32_e32 v0, 0xffff0000, v136
	v_max_f32_e32 v0, v0, v0
	v_max_f32_e32 v0, 0x1e3ce508, v0
	v_rcp_f32_e32 v143, v0
	v_lshlrev_b32_e32 v0, 16, v133
	v_max_f32_e32 v0, v0, v0
	v_max_f32_e32 v132, 0x1e3ce508, v0
	v_lshlrev_b32_e32 v0, 16, v137
	v_max_f32_e32 v0, v0, v0
	v_max_f32_e32 v0, 0x1e3ce508, v0
	v_rcp_f32_e32 v136, v0
	v_and_b32_e32 v0, 0xffff0000, v133
	v_max_f32_e32 v0, v0, v0
	v_max_f32_e32 v133, 0x1e3ce508, v0
	v_and_b32_e32 v0, 0xffff0000, v137
	v_max_f32_e32 v0, v0, v0
	v_max_f32_e32 v0, 0x1e3ce508, v0
	v_rcp_f32_e32 v137, v0
	v_lshlrev_b32_e32 v0, 16, v134
	v_max_f32_e32 v0, v0, v0
	v_pk_mul_f32 v[164:165], v[164:165], v[166:167]
	v_pk_mul_f32 v[132:133], v[132:133], v[136:137]
	v_pk_mul_f32 v[120:121], v[120:121], v[180:181]
	v_pk_mul_f32 v[74:75], v[74:75], v[132:133]
	v_max_f32_e32 v132, 0x1e3ce508, v0
	v_lshlrev_b32_e32 v0, 16, v138
	v_max_f32_e32 v0, v0, v0
	v_max_f32_e32 v0, 0x1e3ce508, v0
	v_rcp_f32_e32 v136, v0
	v_and_b32_e32 v0, 0xffff0000, v134
	v_max_f32_e32 v0, v0, v0
	v_max_f32_e32 v133, 0x1e3ce508, v0
	v_and_b32_e32 v0, 0xffff0000, v138
	v_max_f32_e32 v0, v0, v0
	v_max_f32_e32 v0, 0x1e3ce508, v0
	v_rcp_f32_e32 v137, v0
	v_lshlrev_b32_e32 v0, 16, v135
	v_max_f32_e32 v0, v0, v0
	v_max_f32_e32 v134, 0x1e3ce508, v0
	v_lshlrev_b32_e32 v0, 16, v139
	v_max_f32_e32 v0, v0, v0
	v_max_f32_e32 v0, 0x1e3ce508, v0
	v_rcp_f32_e32 v138, v0
	v_and_b32_e32 v0, 0xffff0000, v135
	v_max_f32_e32 v0, v0, v0
	v_max_f32_e32 v135, 0x1e3ce508, v0
	v_and_b32_e32 v0, 0xffff0000, v139
	v_max_f32_e32 v0, v0, v0
	v_max_f32_e32 v0, 0x1e3ce508, v0
	v_rcp_f32_e32 v139, v0
	v_pk_mul_f32 v[132:133], v[132:133], v[136:137]
	v_pk_mul_f32 v[112:113], v[112:113], v[164:165]
	v_pk_mul_f32 v[68:69], v[68:69], v[132:133]
	v_add_co_u32_e32 v132, vcc, s0, v2
	v_pk_mul_f32 v[134:135], v[134:135], v[138:139]
	s_nop 0
	v_addc_co_u32_e32 v133, vcc, 0, v3, vcc
	s_mov_b32 s0, 0x3e1000
	v_pk_mul_f32 v[70:71], v[70:71], v[134:135]
	v_add_co_u32_e32 v134, vcc, s0, v2
	s_mov_b32 s0, 0x45c000
	s_nop 0
	v_addc_co_u32_e32 v135, vcc, 0, v3, vcc
	global_load_dwordx4 v[192:195], v[134:135], off offset:-4096
	global_load_dwordx4 v[188:191], v[134:135], off
	global_load_dwordx4 v[176:179], v[132:133], off offset:256
	global_load_dwordx4 v[172:175], v[134:135], off offset:256
	v_add_co_u32_e32 v132, vcc, s0, v2
	s_mov_b32 s0, 0x45d000
	s_nop 0
	v_addc_co_u32_e32 v133, vcc, 0, v3, vcc
	v_add_co_u32_e32 v134, vcc, s0, v2
	s_mov_b32 s0, 0x4d8000
	s_nop 0
	v_addc_co_u32_e32 v135, vcc, 0, v3, vcc
	global_load_dwordx4 v[184:187], v[134:135], off offset:-4096
	global_load_dwordx4 v[180:183], v[134:135], off
	global_load_dwordx4 v[168:171], v[132:133], off offset:256
	global_load_dwordx4 v[164:167], v[134:135], off offset:256
	v_add_co_u32_e32 v132, vcc, s0, v2
	s_mov_b32 s0, 0x4d9000
	s_nop 0
	v_addc_co_u32_e32 v133, vcc, 0, v3, vcc
	v_add_co_u32_e32 v134, vcc, s0, v2
	v_pk_mul_f32 v[156:157], v[156:157], v[158:159]
	v_pk_mul_f32 v[148:149], v[148:149], v[150:151]
	v_addc_co_u32_e32 v135, vcc, 0, v3, vcc
	s_mov_b32 s0, 0x554000
	v_pk_mul_f32 v[80:81], v[80:81], v[156:157]
	v_pk_mul_f32 v[104:105], v[104:105], v[148:149]
	global_load_dwordx4 v[160:163], v[134:135], off offset:-4096
	global_load_dwordx4 v[156:159], v[134:135], off
	global_load_dwordx4 v[152:155], v[132:133], off offset:256
	global_load_dwordx4 v[148:151], v[134:135], off offset:256
	v_add_co_u32_e32 v132, vcc, s0, v2
	s_mov_b32 s0, 0x555000
	s_nop 0
	v_addc_co_u32_e32 v133, vcc, 0, v3, vcc
	v_add_co_u32_e32 v2, vcc, s0, v2
	v_pk_mul_f32 v[140:141], v[140:141], v[142:143]
	s_nop 0
	v_addc_co_u32_e32 v3, vcc, 0, v3, vcc
	v_pk_mul_f32 v[72:73], v[72:73], v[140:141]
	global_load_dwordx4 v[144:147], v[2:3], off offset:-4096
	global_load_dwordx4 v[140:143], v[2:3], off
	global_load_dwordx4 v[136:139], v[132:133], off offset:256
	s_nop 0
	global_load_dwordx4 v[132:135], v[2:3], off offset:256
	v_pk_mul_f32 v[210:211], v[210:211], v[212:213]
	s_waitcnt vmcnt(0)
	v_lshlrev_b32_e32 v0, 16, v192
	v_max_f32_e32 v0, v0, v0
	v_max_f32_e32 v2, 0x1e3ce508, v0
	v_lshlrev_b32_e32 v0, 16, v188
	v_max_f32_e32 v0, v0, v0
	v_max_f32_e32 v0, 0x1e3ce508, v0
	v_pk_mul_f32 v[128:129], v[128:129], v[210:211]
	v_rcp_f32_e32 v210, v0
	v_and_b32_e32 v0, 0xffff0000, v192
	v_max_f32_e32 v0, v0, v0
	v_max_f32_e32 v3, 0x1e3ce508, v0
	v_and_b32_e32 v0, 0xffff0000, v188
	v_max_f32_e32 v0, v0, v0
	v_max_f32_e32 v0, 0x1e3ce508, v0
	v_rcp_f32_e32 v211, v0
	v_lshlrev_b32_e32 v0, 16, v193
	v_max_f32_e32 v0, v0, v0
	v_max_f32_e32 v192, 0x1e3ce508, v0
	v_lshlrev_b32_e32 v0, 16, v189
	v_max_f32_e32 v0, v0, v0
	v_max_f32_e32 v0, 0x1e3ce508, v0
	v_rcp_f32_e32 v188, v0
	v_and_b32_e32 v0, 0xffff0000, v193
	v_max_f32_e32 v0, v0, v0
	v_max_f32_e32 v193, 0x1e3ce508, v0
	v_and_b32_e32 v0, 0xffff0000, v189
	v_max_f32_e32 v0, v0, v0
	v_max_f32_e32 v0, 0x1e3ce508, v0
	v_rcp_f32_e32 v189, v0
	v_lshlrev_b32_e32 v0, 16, v194
	v_pk_mul_f32 v[2:3], v[2:3], v[210:211]
	v_max_f32_e32 v0, v0, v0
	v_pk_mul_f32 v[64:65], v[64:65], v[2:3]
	v_max_f32_e32 v2, 0x1e3ce508, v0
	v_lshlrev_b32_e32 v0, 16, v190
	v_max_f32_e32 v0, v0, v0
	v_pk_mul_f32 v[188:189], v[192:193], v[188:189]
	v_max_f32_e32 v0, 0x1e3ce508, v0
	v_pk_mul_f32 v[66:67], v[66:67], v[188:189]
	v_rcp_f32_e32 v188, v0
	v_and_b32_e32 v0, 0xffff0000, v194
	v_max_f32_e32 v0, v0, v0
	v_max_f32_e32 v3, 0x1e3ce508, v0
	v_and_b32_e32 v0, 0xffff0000, v190
	v_max_f32_e32 v0, v0, v0
	v_max_f32_e32 v0, 0x1e3ce508, v0
	v_rcp_f32_e32 v189, v0
	v_lshlrev_b32_e32 v0, 16, v195
	v_max_f32_e32 v0, v0, v0
	v_max_f32_e32 v192, 0x1e3ce508, v0
	v_lshlrev_b32_e32 v0, 16, v191
	v_max_f32_e32 v0, v0, v0
	v_max_f32_e32 v0, 0x1e3ce508, v0
	v_rcp_f32_e32 v190, v0
	v_and_b32_e32 v0, 0xffff0000, v195
	v_max_f32_e32 v0, v0, v0
	v_max_f32_e32 v193, 0x1e3ce508, v0
	v_and_b32_e32 v0, 0xffff0000, v191
	v_max_f32_e32 v0, v0, v0
	v_max_f32_e32 v0, 0x1e3ce508, v0
	v_rcp_f32_e32 v191, v0
	v_lshlrev_b32_e32 v0, 16, v176
	v_pk_mul_f32 v[2:3], v[2:3], v[188:189]
	v_max_f32_e32 v0, v0, v0
	v_pk_mul_f32 v[60:61], v[60:61], v[2:3]
	v_max_f32_e32 v2, 0x1e3ce508, v0
	v_lshlrev_b32_e32 v0, 16, v172
	v_max_f32_e32 v0, v0, v0
	v_pk_mul_f32 v[188:189], v[192:193], v[190:191]
	v_max_f32_e32 v0, 0x1e3ce508, v0
	v_pk_mul_f32 v[62:63], v[62:63], v[188:189]
	v_rcp_f32_e32 v188, v0
	v_and_b32_e32 v0, 0xffff0000, v176
	v_max_f32_e32 v0, v0, v0
	v_max_f32_e32 v3, 0x1e3ce508, v0
	v_and_b32_e32 v0, 0xffff0000, v172
	v_max_f32_e32 v0, v0, v0
	v_max_f32_e32 v0, 0x1e3ce508, v0
	v_rcp_f32_e32 v189, v0
	v_lshlrev_b32_e32 v0, 16, v177
	v_max_f32_e32 v0, v0, v0
	v_max_f32_e32 v176, 0x1e3ce508, v0
	v_lshlrev_b32_e32 v0, 16, v173
	v_max_f32_e32 v0, v0, v0
	v_max_f32_e32 v0, 0x1e3ce508, v0
	v_rcp_f32_e32 v172, v0
	v_and_b32_e32 v0, 0xffff0000, v177
	v_max_f32_e32 v0, v0, v0
	v_max_f32_e32 v177, 0x1e3ce508, v0
	v_and_b32_e32 v0, 0xffff0000, v173
	v_max_f32_e32 v0, v0, v0
	v_max_f32_e32 v0, 0x1e3ce508, v0
	v_rcp_f32_e32 v173, v0
	v_lshlrev_b32_e32 v0, 16, v178
	v_pk_mul_f32 v[2:3], v[2:3], v[188:189]
	v_max_f32_e32 v0, v0, v0
	v_pk_mul_f32 v[32:33], v[32:33], v[2:3]
	v_max_f32_e32 v2, 0x1e3ce508, v0
	v_lshlrev_b32_e32 v0, 16, v174
	v_max_f32_e32 v0, v0, v0
	v_pk_mul_f32 v[172:173], v[176:177], v[172:173]
	v_max_f32_e32 v0, 0x1e3ce508, v0
	v_pk_mul_f32 v[34:35], v[34:35], v[172:173]
	v_rcp_f32_e32 v172, v0
	v_and_b32_e32 v0, 0xffff0000, v178
	v_max_f32_e32 v0, v0, v0
	v_max_f32_e32 v3, 0x1e3ce508, v0
	v_and_b32_e32 v0, 0xffff0000, v174
	v_max_f32_e32 v0, v0, v0
	v_max_f32_e32 v0, 0x1e3ce508, v0
	v_rcp_f32_e32 v173, v0
	v_lshlrev_b32_e32 v0, 16, v179
	v_max_f32_e32 v0, v0, v0
	v_max_f32_e32 v176, 0x1e3ce508, v0
	v_lshlrev_b32_e32 v0, 16, v175
	v_max_f32_e32 v0, v0, v0
	v_max_f32_e32 v0, 0x1e3ce508, v0
	v_rcp_f32_e32 v174, v0
	v_and_b32_e32 v0, 0xffff0000, v179
	v_max_f32_e32 v0, v0, v0
	v_max_f32_e32 v177, 0x1e3ce508, v0
	v_and_b32_e32 v0, 0xffff0000, v175
	v_max_f32_e32 v0, v0, v0
	v_max_f32_e32 v0, 0x1e3ce508, v0
	v_rcp_f32_e32 v175, v0
	v_lshlrev_b32_e32 v0, 16, v184
	v_pk_mul_f32 v[2:3], v[2:3], v[172:173]
	v_max_f32_e32 v0, v0, v0
	v_pk_mul_f32 v[28:29], v[28:29], v[2:3]
	v_max_f32_e32 v2, 0x1e3ce508, v0
	v_lshlrev_b32_e32 v0, 16, v180
	v_max_f32_e32 v0, v0, v0
	v_pk_mul_f32 v[172:173], v[176:177], v[174:175]
	v_max_f32_e32 v0, 0x1e3ce508, v0
	v_pk_mul_f32 v[30:31], v[30:31], v[172:173]
	v_rcp_f32_e32 v172, v0
	v_and_b32_e32 v0, 0xffff0000, v184
	v_max_f32_e32 v0, v0, v0
	v_max_f32_e32 v3, 0x1e3ce508, v0
	v_and_b32_e32 v0, 0xffff0000, v180
	v_max_f32_e32 v0, v0, v0
	v_max_f32_e32 v0, 0x1e3ce508, v0
	v_rcp_f32_e32 v173, v0
	v_lshlrev_b32_e32 v0, 16, v185
	v_max_f32_e32 v0, v0, v0
	v_max_f32_e32 v174, 0x1e3ce508, v0
	v_lshlrev_b32_e32 v0, 16, v181
	v_max_f32_e32 v0, v0, v0
	v_max_f32_e32 v0, 0x1e3ce508, v0
	v_rcp_f32_e32 v176, v0
	v_and_b32_e32 v0, 0xffff0000, v185
	v_max_f32_e32 v0, v0, v0
	v_max_f32_e32 v175, 0x1e3ce508, v0
	v_and_b32_e32 v0, 0xffff0000, v181
	v_max_f32_e32 v0, v0, v0
	v_max_f32_e32 v0, 0x1e3ce508, v0
	v_rcp_f32_e32 v177, v0
	v_lshlrev_b32_e32 v0, 16, v186
	v_pk_mul_f32 v[2:3], v[2:3], v[172:173]
	v_max_f32_e32 v0, v0, v0
	v_pk_mul_f32 v[56:57], v[56:57], v[2:3]
	v_max_f32_e32 v2, 0x1e3ce508, v0
	v_lshlrev_b32_e32 v0, 16, v182
	v_max_f32_e32 v0, v0, v0
	v_pk_mul_f32 v[172:173], v[174:175], v[176:177]
	v_max_f32_e32 v0, 0x1e3ce508, v0
	v_pk_mul_f32 v[58:59], v[58:59], v[172:173]
	v_rcp_f32_e32 v172, v0
	v_and_b32_e32 v0, 0xffff0000, v186
	v_max_f32_e32 v0, v0, v0
	v_max_f32_e32 v3, 0x1e3ce508, v0
	v_and_b32_e32 v0, 0xffff0000, v182
	v_max_f32_e32 v0, v0, v0
	v_max_f32_e32 v0, 0x1e3ce508, v0
	v_rcp_f32_e32 v173, v0
	v_lshlrev_b32_e32 v0, 16, v187
	v_max_f32_e32 v0, v0, v0
	v_max_f32_e32 v174, 0x1e3ce508, v0
	v_lshlrev_b32_e32 v0, 16, v183
	v_max_f32_e32 v0, v0, v0
	v_max_f32_e32 v0, 0x1e3ce508, v0
	v_rcp_f32_e32 v176, v0
	v_and_b32_e32 v0, 0xffff0000, v187
	v_max_f32_e32 v0, v0, v0
	v_max_f32_e32 v175, 0x1e3ce508, v0
	v_and_b32_e32 v0, 0xffff0000, v183
	v_max_f32_e32 v0, v0, v0
	v_max_f32_e32 v0, 0x1e3ce508, v0
	v_rcp_f32_e32 v177, v0
	v_lshlrev_b32_e32 v0, 16, v168
	v_pk_mul_f32 v[2:3], v[2:3], v[172:173]
	v_max_f32_e32 v0, v0, v0
	v_pk_mul_f32 v[52:53], v[52:53], v[2:3]
	v_max_f32_e32 v2, 0x1e3ce508, v0
	v_lshlrev_b32_e32 v0, 16, v164
	v_max_f32_e32 v0, v0, v0
	v_pk_mul_f32 v[172:173], v[174:175], v[176:177]
	v_max_f32_e32 v0, 0x1e3ce508, v0
	v_pk_mul_f32 v[54:55], v[54:55], v[172:173]
	v_rcp_f32_e32 v172, v0
	v_and_b32_e32 v0, 0xffff0000, v168
	v_max_f32_e32 v0, v0, v0
	v_max_f32_e32 v3, 0x1e3ce508, v0
	v_and_b32_e32 v0, 0xffff0000, v164
	v_max_f32_e32 v0, v0, v0
	v_max_f32_e32 v0, 0x1e3ce508, v0
	v_rcp_f32_e32 v173, v0
	v_lshlrev_b32_e32 v0, 16, v169
	v_max_f32_e32 v0, v0, v0
	v_max_f32_e32 v168, 0x1e3ce508, v0
	v_lshlrev_b32_e32 v0, 16, v165
	v_max_f32_e32 v0, v0, v0
	v_max_f32_e32 v0, 0x1e3ce508, v0
	v_rcp_f32_e32 v164, v0
	v_and_b32_e32 v0, 0xffff0000, v169
	v_max_f32_e32 v0, v0, v0
	v_max_f32_e32 v169, 0x1e3ce508, v0
	v_and_b32_e32 v0, 0xffff0000, v165
	v_max_f32_e32 v0, v0, v0
	v_max_f32_e32 v0, 0x1e3ce508, v0
	v_rcp_f32_e32 v165, v0
	v_lshlrev_b32_e32 v0, 16, v170
	v_pk_mul_f32 v[2:3], v[2:3], v[172:173]
	v_max_f32_e32 v0, v0, v0
	v_pk_mul_f32 v[24:25], v[24:25], v[2:3]
	v_max_f32_e32 v2, 0x1e3ce508, v0
	v_lshlrev_b32_e32 v0, 16, v166
	v_max_f32_e32 v0, v0, v0
	v_pk_mul_f32 v[164:165], v[168:169], v[164:165]
	v_max_f32_e32 v0, 0x1e3ce508, v0
	v_pk_mul_f32 v[26:27], v[26:27], v[164:165]
	v_rcp_f32_e32 v164, v0
	v_and_b32_e32 v0, 0xffff0000, v170
	v_max_f32_e32 v0, v0, v0
	v_max_f32_e32 v3, 0x1e3ce508, v0
	v_and_b32_e32 v0, 0xffff0000, v166
	v_max_f32_e32 v0, v0, v0
	v_max_f32_e32 v0, 0x1e3ce508, v0
	v_rcp_f32_e32 v165, v0
	v_lshlrev_b32_e32 v0, 16, v171
	v_max_f32_e32 v0, v0, v0
	v_max_f32_e32 v168, 0x1e3ce508, v0
	v_lshlrev_b32_e32 v0, 16, v167
	v_max_f32_e32 v0, v0, v0
	v_max_f32_e32 v0, 0x1e3ce508, v0
	v_rcp_f32_e32 v166, v0
	v_and_b32_e32 v0, 0xffff0000, v171
	v_max_f32_e32 v0, v0, v0
	v_max_f32_e32 v169, 0x1e3ce508, v0
	v_and_b32_e32 v0, 0xffff0000, v167
	v_max_f32_e32 v0, v0, v0
	v_max_f32_e32 v0, 0x1e3ce508, v0
	v_rcp_f32_e32 v167, v0
	v_lshlrev_b32_e32 v0, 16, v160
	v_pk_mul_f32 v[2:3], v[2:3], v[164:165]
	v_max_f32_e32 v0, v0, v0
	v_pk_mul_f32 v[20:21], v[20:21], v[2:3]
	v_max_f32_e32 v2, 0x1e3ce508, v0
	v_lshlrev_b32_e32 v0, 16, v156
	v_max_f32_e32 v0, v0, v0
	v_pk_mul_f32 v[164:165], v[168:169], v[166:167]
	v_max_f32_e32 v0, 0x1e3ce508, v0
	v_pk_mul_f32 v[22:23], v[22:23], v[164:165]
	v_rcp_f32_e32 v164, v0
	v_and_b32_e32 v0, 0xffff0000, v160
	v_max_f32_e32 v0, v0, v0
	v_max_f32_e32 v3, 0x1e3ce508, v0
	v_and_b32_e32 v0, 0xffff0000, v156
	v_max_f32_e32 v0, v0, v0
	v_max_f32_e32 v0, 0x1e3ce508, v0
	v_rcp_f32_e32 v165, v0
	v_lshlrev_b32_e32 v0, 16, v161
	v_max_f32_e32 v0, v0, v0
	v_max_f32_e32 v160, 0x1e3ce508, v0
	v_lshlrev_b32_e32 v0, 16, v157
	v_max_f32_e32 v0, v0, v0
	v_max_f32_e32 v0, 0x1e3ce508, v0
	v_rcp_f32_e32 v156, v0
	v_and_b32_e32 v0, 0xffff0000, v161
	v_max_f32_e32 v0, v0, v0
	v_max_f32_e32 v161, 0x1e3ce508, v0
	v_and_b32_e32 v0, 0xffff0000, v157
	v_max_f32_e32 v0, v0, v0
	v_max_f32_e32 v0, 0x1e3ce508, v0
	v_rcp_f32_e32 v157, v0
	v_lshlrev_b32_e32 v0, 16, v162
	v_pk_mul_f32 v[2:3], v[2:3], v[164:165]
	v_max_f32_e32 v0, v0, v0
	v_pk_mul_f32 v[48:49], v[48:49], v[2:3]
	v_max_f32_e32 v2, 0x1e3ce508, v0
	v_lshlrev_b32_e32 v0, 16, v158
	v_max_f32_e32 v0, v0, v0
	v_pk_mul_f32 v[156:157], v[160:161], v[156:157]
	v_max_f32_e32 v0, 0x1e3ce508, v0
	v_pk_mul_f32 v[50:51], v[50:51], v[156:157]
	v_rcp_f32_e32 v156, v0
	v_and_b32_e32 v0, 0xffff0000, v162
	v_max_f32_e32 v0, v0, v0
	v_max_f32_e32 v3, 0x1e3ce508, v0
	v_and_b32_e32 v0, 0xffff0000, v158
	v_max_f32_e32 v0, v0, v0
	v_max_f32_e32 v0, 0x1e3ce508, v0
	v_rcp_f32_e32 v157, v0
	v_lshlrev_b32_e32 v0, 16, v163
	v_max_f32_e32 v0, v0, v0
	v_max_f32_e32 v160, 0x1e3ce508, v0
	v_lshlrev_b32_e32 v0, 16, v159
	v_max_f32_e32 v0, v0, v0
	v_max_f32_e32 v0, 0x1e3ce508, v0
	v_rcp_f32_e32 v158, v0
	v_and_b32_e32 v0, 0xffff0000, v163
	v_max_f32_e32 v0, v0, v0
	v_max_f32_e32 v161, 0x1e3ce508, v0
	v_and_b32_e32 v0, 0xffff0000, v159
	v_max_f32_e32 v0, v0, v0
	v_max_f32_e32 v0, 0x1e3ce508, v0
	v_rcp_f32_e32 v159, v0
	v_lshlrev_b32_e32 v0, 16, v152
	v_pk_mul_f32 v[2:3], v[2:3], v[156:157]
	v_max_f32_e32 v0, v0, v0
	v_pk_mul_f32 v[44:45], v[44:45], v[2:3]
	v_max_f32_e32 v2, 0x1e3ce508, v0
	v_lshlrev_b32_e32 v0, 16, v148
	v_max_f32_e32 v0, v0, v0
	v_pk_mul_f32 v[156:157], v[160:161], v[158:159]
	v_max_f32_e32 v0, 0x1e3ce508, v0
	v_pk_mul_f32 v[46:47], v[46:47], v[156:157]
	v_rcp_f32_e32 v156, v0
	v_and_b32_e32 v0, 0xffff0000, v152
	v_max_f32_e32 v0, v0, v0
	v_max_f32_e32 v3, 0x1e3ce508, v0
	v_and_b32_e32 v0, 0xffff0000, v148
	v_max_f32_e32 v0, v0, v0
	v_max_f32_e32 v0, 0x1e3ce508, v0
	v_rcp_f32_e32 v157, v0
	v_lshlrev_b32_e32 v0, 16, v153
	v_max_f32_e32 v0, v0, v0
	v_max_f32_e32 v152, 0x1e3ce508, v0
	v_lshlrev_b32_e32 v0, 16, v149
	v_max_f32_e32 v0, v0, v0
	v_max_f32_e32 v0, 0x1e3ce508, v0
	v_rcp_f32_e32 v148, v0
	v_and_b32_e32 v0, 0xffff0000, v153
	v_max_f32_e32 v0, v0, v0
	v_max_f32_e32 v153, 0x1e3ce508, v0
	v_and_b32_e32 v0, 0xffff0000, v149
	v_max_f32_e32 v0, v0, v0
	v_max_f32_e32 v0, 0x1e3ce508, v0
	v_rcp_f32_e32 v149, v0
	v_lshlrev_b32_e32 v0, 16, v154
	v_pk_mul_f32 v[2:3], v[2:3], v[156:157]
	v_max_f32_e32 v0, v0, v0
	v_pk_mul_f32 v[16:17], v[16:17], v[2:3]
	v_max_f32_e32 v2, 0x1e3ce508, v0
	v_lshlrev_b32_e32 v0, 16, v150
	v_max_f32_e32 v0, v0, v0
	v_pk_mul_f32 v[148:149], v[152:153], v[148:149]
	v_max_f32_e32 v0, 0x1e3ce508, v0
	v_pk_mul_f32 v[18:19], v[18:19], v[148:149]
	v_rcp_f32_e32 v148, v0
	v_and_b32_e32 v0, 0xffff0000, v154
	v_max_f32_e32 v0, v0, v0
	v_max_f32_e32 v3, 0x1e3ce508, v0
	v_and_b32_e32 v0, 0xffff0000, v150
	v_max_f32_e32 v0, v0, v0
	v_max_f32_e32 v0, 0x1e3ce508, v0
	v_rcp_f32_e32 v149, v0
	v_lshlrev_b32_e32 v0, 16, v155
	v_max_f32_e32 v0, v0, v0
	v_max_f32_e32 v152, 0x1e3ce508, v0
	v_lshlrev_b32_e32 v0, 16, v151
	v_max_f32_e32 v0, v0, v0
	v_max_f32_e32 v0, 0x1e3ce508, v0
	v_rcp_f32_e32 v150, v0
	v_and_b32_e32 v0, 0xffff0000, v155
	v_max_f32_e32 v0, v0, v0
	v_max_f32_e32 v153, 0x1e3ce508, v0
	v_and_b32_e32 v0, 0xffff0000, v151
	v_max_f32_e32 v0, v0, v0
	v_max_f32_e32 v0, 0x1e3ce508, v0
	v_rcp_f32_e32 v151, v0
	v_lshlrev_b32_e32 v0, 16, v144
	v_pk_mul_f32 v[2:3], v[2:3], v[148:149]
	v_max_f32_e32 v0, v0, v0
	v_pk_mul_f32 v[12:13], v[12:13], v[2:3]
	v_max_f32_e32 v2, 0x1e3ce508, v0
	v_lshlrev_b32_e32 v0, 16, v140
	v_max_f32_e32 v0, v0, v0
	v_pk_mul_f32 v[148:149], v[152:153], v[150:151]
	v_max_f32_e32 v0, 0x1e3ce508, v0
	v_pk_mul_f32 v[14:15], v[14:15], v[148:149]
	v_rcp_f32_e32 v148, v0
	v_and_b32_e32 v0, 0xffff0000, v144
	v_max_f32_e32 v0, v0, v0
	v_max_f32_e32 v3, 0x1e3ce508, v0
	v_and_b32_e32 v0, 0xffff0000, v140
	v_max_f32_e32 v0, v0, v0
	v_max_f32_e32 v0, 0x1e3ce508, v0
	v_rcp_f32_e32 v149, v0
	v_lshlrev_b32_e32 v0, 16, v145
	v_max_f32_e32 v0, v0, v0
	v_max_f32_e32 v144, 0x1e3ce508, v0
	v_lshlrev_b32_e32 v0, 16, v141
	v_max_f32_e32 v0, v0, v0
	v_max_f32_e32 v0, 0x1e3ce508, v0
	v_rcp_f32_e32 v140, v0
	v_and_b32_e32 v0, 0xffff0000, v145
	v_max_f32_e32 v0, v0, v0
	v_max_f32_e32 v145, 0x1e3ce508, v0
	v_and_b32_e32 v0, 0xffff0000, v141
	v_max_f32_e32 v0, v0, v0
	v_max_f32_e32 v0, 0x1e3ce508, v0
	v_rcp_f32_e32 v141, v0
	v_lshlrev_b32_e32 v0, 16, v146
	v_pk_mul_f32 v[2:3], v[2:3], v[148:149]
	v_max_f32_e32 v0, v0, v0
	v_pk_mul_f32 v[40:41], v[40:41], v[2:3]
	v_max_f32_e32 v2, 0x1e3ce508, v0
	v_lshlrev_b32_e32 v0, 16, v142
	v_max_f32_e32 v0, v0, v0
	v_pk_mul_f32 v[140:141], v[144:145], v[140:141]
	v_max_f32_e32 v0, 0x1e3ce508, v0
	v_pk_mul_f32 v[42:43], v[42:43], v[140:141]
	v_rcp_f32_e32 v140, v0
	v_and_b32_e32 v0, 0xffff0000, v146
	v_max_f32_e32 v0, v0, v0
	v_max_f32_e32 v3, 0x1e3ce508, v0
	v_and_b32_e32 v0, 0xffff0000, v142
	v_max_f32_e32 v0, v0, v0
	v_max_f32_e32 v0, 0x1e3ce508, v0
	v_rcp_f32_e32 v141, v0
	v_lshlrev_b32_e32 v0, 16, v147
	v_max_f32_e32 v0, v0, v0
	v_max_f32_e32 v144, 0x1e3ce508, v0
	v_lshlrev_b32_e32 v0, 16, v143
	v_max_f32_e32 v0, v0, v0
	v_max_f32_e32 v0, 0x1e3ce508, v0
	v_rcp_f32_e32 v142, v0
	v_and_b32_e32 v0, 0xffff0000, v147
	v_max_f32_e32 v0, v0, v0
	v_max_f32_e32 v145, 0x1e3ce508, v0
	v_and_b32_e32 v0, 0xffff0000, v143
	v_max_f32_e32 v0, v0, v0
	v_max_f32_e32 v0, 0x1e3ce508, v0
	v_rcp_f32_e32 v143, v0
	v_lshlrev_b32_e32 v0, 16, v136
	v_pk_mul_f32 v[2:3], v[2:3], v[140:141]
	v_max_f32_e32 v0, v0, v0
	v_pk_mul_f32 v[36:37], v[36:37], v[2:3]
	v_max_f32_e32 v2, 0x1e3ce508, v0
	v_lshlrev_b32_e32 v0, 16, v132
	v_max_f32_e32 v0, v0, v0
	v_pk_mul_f32 v[140:141], v[144:145], v[142:143]
	v_max_f32_e32 v0, 0x1e3ce508, v0
	v_pk_mul_f32 v[38:39], v[38:39], v[140:141]
	v_rcp_f32_e32 v140, v0
	v_and_b32_e32 v0, 0xffff0000, v136
	v_max_f32_e32 v0, v0, v0
	v_max_f32_e32 v3, 0x1e3ce508, v0
	v_and_b32_e32 v0, 0xffff0000, v132
	v_max_f32_e32 v0, v0, v0
	v_max_f32_e32 v0, 0x1e3ce508, v0
	v_rcp_f32_e32 v141, v0
	v_lshlrev_b32_e32 v0, 16, v137
	v_max_f32_e32 v0, v0, v0
	v_max_f32_e32 v136, 0x1e3ce508, v0
	v_lshlrev_b32_e32 v0, 16, v133
	v_max_f32_e32 v0, v0, v0
	v_max_f32_e32 v0, 0x1e3ce508, v0
	v_rcp_f32_e32 v132, v0
	v_and_b32_e32 v0, 0xffff0000, v137
	v_max_f32_e32 v0, v0, v0
	v_max_f32_e32 v137, 0x1e3ce508, v0
	v_and_b32_e32 v0, 0xffff0000, v133
	v_max_f32_e32 v0, v0, v0
	v_max_f32_e32 v0, 0x1e3ce508, v0
	v_rcp_f32_e32 v133, v0
	v_lshlrev_b32_e32 v0, 16, v138
	v_pk_mul_f32 v[2:3], v[2:3], v[140:141]
	v_max_f32_e32 v0, v0, v0
	v_pk_mul_f32 v[8:9], v[8:9], v[2:3]
	v_max_f32_e32 v2, 0x1e3ce508, v0
	v_lshlrev_b32_e32 v0, 16, v134
	v_max_f32_e32 v0, v0, v0
	v_pk_mul_f32 v[132:133], v[136:137], v[132:133]
	v_max_f32_e32 v0, 0x1e3ce508, v0
	v_pk_mul_f32 v[10:11], v[10:11], v[132:133]
	v_rcp_f32_e32 v132, v0
	v_and_b32_e32 v0, 0xffff0000, v138
	v_max_f32_e32 v0, v0, v0
	v_max_f32_e32 v3, 0x1e3ce508, v0
	v_and_b32_e32 v0, 0xffff0000, v134
	v_max_f32_e32 v0, v0, v0
	v_max_f32_e32 v0, 0x1e3ce508, v0
	v_rcp_f32_e32 v133, v0
	v_lshlrev_b32_e32 v0, 16, v139
	v_max_f32_e32 v0, v0, v0
	v_max_f32_e32 v136, 0x1e3ce508, v0
	v_lshlrev_b32_e32 v0, 16, v135
	v_max_f32_e32 v0, v0, v0
	v_max_f32_e32 v0, 0x1e3ce508, v0
	v_rcp_f32_e32 v134, v0
	v_and_b32_e32 v0, 0xffff0000, v139
	v_max_f32_e32 v0, v0, v0
	v_max_f32_e32 v137, 0x1e3ce508, v0
	v_and_b32_e32 v0, 0xffff0000, v135
	v_max_f32_e32 v0, v0, v0
	v_max_f32_e32 v0, 0x1e3ce508, v0
	v_rcp_f32_e32 v135, v0
	v_pk_mul_f32 v[2:3], v[2:3], v[132:133]
	v_pk_mul_f32 v[132:133], v[136:137], v[134:135]
	s_nop 0
	v_pk_mul_f32 v[6:7], v[6:7], v[132:133]
	v_pk_mul_f32 v[4:5], v[4:5], v[2:3]
	s_and_b64 vcc, exec, s[34:35]
	s_mov_b64 s[0:1], -1
	s_cbranch_vccnz .LBB0_1222
